# scan steady state as a 16-chunk loop (smaller code), prefix-tail loads issued at unit entry
# baseline (speedup 1.0000x reference)
.LBB0_1114:
	s_mov_b64 s[68:69], 0
	s_and_b64 vcc, exec, s[0:1]
	s_mov_b64 s[0:1], 0
	s_cbranch_vccz .LBB0_1243
	s_add_i32 s8, s63, 0xfffffde0
	s_lshr_b32 s9, s8, 3
	s_and_b32 s8, s8, 7
	s_add_i32 s8, s8, s9
	s_and_b32 s8, s8, 7
	s_lshl_b32 s9, s9, 7
	s_or_b32 s8, s9, s8
	s_lshl_b32 s8, s8, 2
	s_add_u32 s8, s88, s8
	s_addc_u32 s9, s89, 0
	global_load_dword v112, v82, s[8:9]
	global_load_dword v113, v82, s[8:9] offset:32
	global_load_dword v114, v82, s[8:9] offset:64
	global_load_dword v115, v82, s[8:9] offset:96
	global_load_dword v116, v82, s[8:9] offset:128
	global_load_dword v117, v82, s[8:9] offset:160
	global_load_dword v118, v82, s[8:9] offset:192
	global_load_dword v119, v82, s[8:9] offset:224
	global_load_dword v120, v82, s[8:9] offset:256
	global_load_dword v121, v82, s[8:9] offset:288
	global_load_dword v122, v82, s[8:9] offset:320
	global_load_dword v123, v82, s[8:9] offset:352
	global_load_dword v124, v82, s[8:9] offset:384
	global_load_dword v125, v82, s[8:9] offset:416
	global_load_dword v126, v82, s[8:9] offset:448
	global_load_dword v127, v82, s[8:9] offset:480
	s_add_i32 s0, s63, 0xfffffde0
	s_lshr_b32 s60, s0, 3
	s_lshl_b32 s92, s60, 14
	v_readlane_b32 s12, v254, 29
	s_and_b32 s10, s63, 7
	s_add_i32 s10, s10, s60
	s_and_b32 s10, s10, 7
	s_lshl_b64 s[0:1], s[92:93], 2
	v_readlane_b32 s20, v254, 37
	v_mov_b32_e32 v105, v0
	v_readlane_b32 s21, v254, 38
	s_add_u32 s0, s20, s0
	s_addc_u32 s1, s21, s1
	s_lshl_b32 s2, s10, 2
	v_lshlrev_b32_e32 v2, 2, v105
	s_add_u32 s0, s0, s2
	v_ashrrev_i32_e32 v3, 31, v2
	s_addc_u32 s1, s1, 0
	v_lshlrev_b64 v[4:5], 5, v[2:3]
	v_lshl_add_u64 v[4:5], s[0:1], 0, v[4:5]
	global_load_dword v6, v[4:5], off
	v_or_b32_e32 v4, 1, v2
	v_ashrrev_i32_e32 v5, 31, v4
	v_lshlrev_b64 v[4:5], 5, v[4:5]
	v_lshl_add_u64 v[4:5], s[0:1], 0, v[4:5]
	global_load_dword v7, v[4:5], off
	v_or_b32_e32 v4, 2, v2
	v_ashrrev_i32_e32 v5, 31, v4
	v_or_b32_e32 v2, 3, v2
	v_lshlrev_b64 v[4:5], 5, v[4:5]
	v_ashrrev_i32_e32 v3, 31, v2
	v_lshl_add_u64 v[4:5], s[0:1], 0, v[4:5]
	v_lshlrev_b64 v[2:3], 5, v[2:3]
	global_load_dword v8, v[4:5], off
	v_lshl_add_u64 v[2:3], s[0:1], 0, v[2:3]
	global_load_dword v3, v[2:3], off
	s_add_i32 s34, s63, 0xfffffde0
	s_lshr_b32 s70, s34, 3
	s_and_b32 s71, s34, 7
	s_add_i32 s71, s71, s70
	s_and_b32 s71, s71, 7
	v_lshrrev_b32_e32 v80, 6, v0
	v_and_b32_e32 v77, 15, v0
	v_bfe_u32 v76, v0, 4, 2
	v_readfirstlane_b32 s72, v80
	v_readlane_b32 s34, v254, 33
	v_readlane_b32 s35, v254, 34
	v_readlane_b32 s36, v254, 35
	v_readlane_b32 s37, v254, 36
	v_lshlrev_b32_e32 v72, 11, v76
	v_lshl_add_u32 v72, v77, 4, v72
	v_add_u32_e32 v73, 0x2000, v72
	v_add_u32_e32 v74, 0x4000, v72
	v_add_u32_e32 v75, 0x6000, v72
	v_lshlrev_b32_e32 v81, 10, v77
	v_lshl_add_u32 v81, v76, 4, v81
	s_lshl_b32 s38, s70, 22
	s_lshl_b32 s39, s71, 8
	s_add_i32 s38, s38, s39
	s_lshl_b32 s39, s72, 15
	s_add_i32 s38, s38, s39
	s_add_u32 s74, s34, s38
	s_addc_u32 s75, s35, 0
	s_add_u32 s76, s36, s38
	s_addc_u32 s77, s37, 0
	s_add_u32 s78, s76, 0x40000
	s_addc_u32 s79, s77, 0
	s_lshl_b32 s38, s70, 14
	s_lshl_b32 s39, s71, 7
	s_add_i32 s38, s38, s39
	s_add_i32 s39, s38, 0x7faea00
	s_add_u32 s80, s90, s39
	s_addc_u32 s81, s91, 0
	s_add_i32 s39, s38, 0x1e2ea00
	s_add_u32 s86, s90, s39
	s_addc_u32 s87, s91, 0
	s_lshl_b32 s38, s70, 15
	s_lshl_b32 s39, s71, 8
	s_add_i32 s38, s38, s39
	s_add_i32 s39, s38, 0x821c000
	s_add_u32 s82, s88, s39
	s_addc_u32 s83, s89, 0
	s_add_i32 s39, s38, 0x829c000
	s_add_u32 s84, s88, s39
	s_addc_u32 s85, s89, 0
	s_lshl_b32 s73, s72, 13
	s_add_i32 s73, s73, 0xd400
	global_load_dwordx4 v[64:67], v81, s[80:81]
	global_load_dwordx4 v[68:71], v81, s[80:81] offset:64
	s_cmp_lg_u32 s72, 0
	s_cbranch_scc1 .Lsa_pre_nz
	global_load_dwordx4 v[232:235], v72, s[82:83] nt
	global_load_dwordx4 v[236:239], v73, s[82:83] nt
	global_load_dwordx4 v[240:243], v74, s[82:83] nt
	global_load_dwordx4 v[244:247], v75, s[82:83] nt

.LBB0_1127:
	s_or_b64 exec, exec, s[0:1]
	v_pk_add_f32 v[4:5], v[4:5], v[6:7] op_sel_hi:[1,0]
	v_pk_add_f32 v[2:3], v[2:3], v[6:7] op_sel_hi:[1,0]
	s_lshl_b32 s4, s60, 7
	v_lshl_add_u32 v8, v105, 4, 16
	v_pk_mul_f32 v[4:5], v[4:5], s[62:63] op_sel_hi:[1,0]
	v_pk_mul_f32 v[6:7], v[2:3], s[62:63] op_sel_hi:[1,0]
	v_cmp_eq_u32_e32 vcc, s30, v105
	ds_write_b128 v8, v[4:7]
	s_and_saveexec_b64 s[0:1], vcc
	s_cbranch_execz .LBB0_1129
	s_or_b32 s2, s4, s10
	s_mov_b32 s3, s93
	s_lshl_b64 s[2:3], s[2:3], 2
	s_add_u32 s2, s88, s2
	s_addc_u32 s3, s89, s3
	s_waitcnt vmcnt(22)
	v_add_f32_e32 v112, v3, v112
	v_add_f32_e32 v113, v112, v113
	v_add_f32_e32 v114, v113, v114
	v_add_f32_e32 v115, v114, v115
	v_add_f32_e32 v116, v115, v116
	v_add_f32_e32 v117, v116, v117
	v_add_f32_e32 v118, v117, v118
	v_add_f32_e32 v119, v118, v119
	v_add_f32_e32 v120, v119, v120
	v_add_f32_e32 v121, v120, v121
	v_add_f32_e32 v122, v121, v122
	v_add_f32_e32 v123, v122, v123
	v_add_f32_e32 v124, v123, v124
	v_add_f32_e32 v125, v124, v125
	v_add_f32_e32 v126, v125, v126
	v_add_f32_e32 v127, v126, v127
	v_pk_mul_f32 v[112:113], v[112:113], s[62:63] op_sel_hi:[1,0]
	v_pk_mul_f32 v[114:115], v[114:115], s[62:63] op_sel_hi:[1,0]
	v_pk_mul_f32 v[116:117], v[116:117], s[62:63] op_sel_hi:[1,0]
	v_pk_mul_f32 v[118:119], v[118:119], s[62:63] op_sel_hi:[1,0]
	v_pk_mul_f32 v[120:121], v[120:121], s[62:63] op_sel_hi:[1,0]
	v_pk_mul_f32 v[122:123], v[122:123], s[62:63] op_sel_hi:[1,0]
	v_pk_mul_f32 v[124:125], v[124:125], s[62:63] op_sel_hi:[1,0]
	v_pk_mul_f32 v[126:127], v[126:127], s[62:63] op_sel_hi:[1,0]
	ds_write_b128 v100, v[112:115] offset:8192
	ds_write_b128 v100, v[116:119] offset:8208
	ds_write_b128 v100, v[120:123] offset:8224
	ds_write_b128 v100, v[124:127] offset:8240

.LBB0_1888:
	v_lshrrev_b32_e32 v4, 1, v75
	v_ashrrev_i32_e32 v6, 15, v74
	v_bfe_u32 v9, v4, 12, 3
	v_ashrrev_i32_e32 v7, 31, v6
	v_bfe_u32 v8, v75, 1, 15
	v_lshlrev_b64 v[4:5], 25, v[6:7]
	v_lshl_or_b32 v68, v6, 10, v9
	v_lshl_or_b32 v4, v8, 3, v4
	v_or_b32_e32 v6, 0xf8, v68
	v_or_b32_e32 v8, 0xf0, v68
	v_or_b32_e32 v10, 0xe8, v68
	v_or_b32_e32 v12, 0xe0, v68
	v_or_b32_e32 v14, 0xd8, v68
	v_or_b32_e32 v16, 0xd0, v68
	v_or_b32_e32 v18, 0xc8, v68
	v_or_b32_e32 v20, 0xc0, v68
	v_or_b32_e32 v22, 0xb8, v68
	v_or_b32_e32 v24, 0xb0, v68
	v_or_b32_e32 v26, 0xa8, v68
	v_or_b32_e32 v28, 0xa0, v68
	v_or_b32_e32 v30, 0x98, v68
	v_or_b32_e32 v32, 0x90, v68
	v_or_b32_e32 v34, 0x88, v68
	v_or_b32_e32 v36, 0x80, v68
	v_or_b32_e32 v38, 0x78, v68
	v_or_b32_e32 v40, 0x70, v68
	v_or_b32_e32 v42, 0x68, v68
	v_or_b32_e32 v44, 0x60, v68
	v_or_b32_e32 v46, 0x58, v68
	v_or_b32_e32 v48, 0x50, v68
	v_or_b32_e32 v50, 0x48, v68
	v_or_b32_e32 v52, 64, v68
	v_or_b32_e32 v54, 56, v68
	v_or_b32_e32 v56, 48, v68
	v_or_b32_e32 v58, 40, v68
	v_or_b32_e32 v60, 32, v68
	v_or_b32_e32 v62, 24, v68
	v_or_b32_e32 v64, 16, v68
	v_or_b32_e32 v66, 8, v68
	v_ashrrev_i32_e32 v7, 31, v6
	v_ashrrev_i32_e32 v9, 31, v8
	v_ashrrev_i32_e32 v11, 31, v10
	v_ashrrev_i32_e32 v13, 31, v12
	v_ashrrev_i32_e32 v15, 31, v14
	v_ashrrev_i32_e32 v17, 31, v16
	v_ashrrev_i32_e32 v19, 31, v18
	v_ashrrev_i32_e32 v21, 31, v20
	v_ashrrev_i32_e32 v23, 31, v22
	v_ashrrev_i32_e32 v25, 31, v24
	v_ashrrev_i32_e32 v27, 31, v26
	v_ashrrev_i32_e32 v29, 31, v28
	v_ashrrev_i32_e32 v31, 31, v30
	v_ashrrev_i32_e32 v33, 31, v32
	v_ashrrev_i32_e32 v35, 31, v34
	v_ashrrev_i32_e32 v37, 31, v36
	v_ashrrev_i32_e32 v39, 31, v38
	v_ashrrev_i32_e32 v41, 31, v40
	v_ashrrev_i32_e32 v43, 31, v42
	v_ashrrev_i32_e32 v45, 31, v44
	v_ashrrev_i32_e32 v47, 31, v46
	v_ashrrev_i32_e32 v49, 31, v48
	v_ashrrev_i32_e32 v51, 31, v50
	v_ashrrev_i32_e32 v53, 31, v52
	v_ashrrev_i32_e32 v55, 31, v54
	v_ashrrev_i32_e32 v57, 31, v56
	v_ashrrev_i32_e32 v59, 31, v58
	v_ashrrev_i32_e32 v61, 31, v60
	v_ashrrev_i32_e32 v63, 31, v62
	v_ashrrev_i32_e32 v65, 31, v64
	v_ashrrev_i32_e32 v67, 31, v66
	v_ashrrev_i32_e32 v69, 31, v68
	v_mov_b32_e32 v72, 0
	v_lshl_add_u64 v[4:5], s[88:89], 0, v[4:5]
	v_lshl_add_u64 v[6:7], v[6:7], 2, v[2:3]
	v_lshl_add_u64 v[8:9], v[8:9], 2, v[2:3]
	v_lshl_add_u64 v[10:11], v[10:11], 2, v[2:3]
	v_lshl_add_u64 v[12:13], v[12:13], 2, v[2:3]
	v_lshl_add_u64 v[14:15], v[14:15], 2, v[2:3]
	v_lshl_add_u64 v[16:17], v[16:17], 2, v[2:3]
	v_lshl_add_u64 v[18:19], v[18:19], 2, v[2:3]
	v_lshl_add_u64 v[20:21], v[20:21], 2, v[2:3]
	v_lshl_add_u64 v[22:23], v[22:23], 2, v[2:3]
	v_lshl_add_u64 v[24:25], v[24:25], 2, v[2:3]
	v_lshl_add_u64 v[26:27], v[26:27], 2, v[2:3]
	v_lshl_add_u64 v[28:29], v[28:29], 2, v[2:3]
	v_lshl_add_u64 v[30:31], v[30:31], 2, v[2:3]
	v_lshl_add_u64 v[32:33], v[32:33], 2, v[2:3]
	v_lshl_add_u64 v[34:35], v[34:35], 2, v[2:3]
	v_lshl_add_u64 v[36:37], v[36:37], 2, v[2:3]
	v_lshl_add_u64 v[38:39], v[38:39], 2, v[2:3]
	v_lshl_add_u64 v[40:41], v[40:41], 2, v[2:3]
	v_lshl_add_u64 v[42:43], v[42:43], 2, v[2:3]
	v_lshl_add_u64 v[44:45], v[44:45], 2, v[2:3]
	v_lshl_add_u64 v[46:47], v[46:47], 2, v[2:3]
	v_lshl_add_u64 v[48:49], v[48:49], 2, v[2:3]
	v_lshl_add_u64 v[50:51], v[50:51], 2, v[2:3]
	v_lshl_add_u64 v[52:53], v[52:53], 2, v[2:3]
	v_lshl_add_u64 v[54:55], v[54:55], 2, v[2:3]
	v_lshl_add_u64 v[56:57], v[56:57], 2, v[2:3]
	v_lshl_add_u64 v[58:59], v[58:59], 2, v[2:3]
	v_lshl_add_u64 v[60:61], v[60:61], 2, v[2:3]
	v_lshl_add_u64 v[62:63], v[62:63], 2, v[2:3]
	v_lshl_add_u64 v[64:65], v[64:65], 2, v[2:3]
	v_lshl_add_u64 v[66:67], v[66:67], 2, v[2:3]
	v_lshl_add_u64 v[68:69], v[68:69], 2, v[2:3]
	s_mov_b64 s[10:11], s[90:91]
	s_mov_b64 s[12:13], 0
	v_mov_b32_e32 v73, v72
	v_and_b32_e32 v6, 63, v0
	v_lshlrev_b32_e32 v6, 5, v6
	v_mov_b32_e32 v7, 0
	v_lshl_add_u64 v[6:7], v[68:69], 0, v[6:7]
	v_lshl_add_u64 v[6:7], s[90:91], 0, v[6:7]
	global_load_dword v8, v[6:7], off
	global_load_dword v9, v[6:7], off offset:2048
	s_mov_b64 s[12:13], 0x400000
	v_lshl_add_u64 v[44:45], v[4:5], 0, s[12:13]
	s_mov_b64 s[12:13], 0
	global_load_dwordx2 v[10:11], v[4:5], off
	s_add_u32 s12, s12, 0x40000
	s_addc_u32 s13, s13, 0
	v_lshl_add_u64 v[42:43], v[4:5], 0, s[12:13]
	global_load_dwordx2 v[12:13], v[42:43], off
	s_add_u32 s12, s12, 0x40000
	s_addc_u32 s13, s13, 0
	v_lshl_add_u64 v[42:43], v[4:5], 0, s[12:13]
	global_load_dwordx2 v[14:15], v[42:43], off
	s_add_u32 s12, s12, 0x40000
	s_addc_u32 s13, s13, 0
	v_lshl_add_u64 v[42:43], v[4:5], 0, s[12:13]
	global_load_dwordx2 v[16:17], v[42:43], off
	s_add_u32 s12, s12, 0x40000
	s_addc_u32 s13, s13, 0
	v_lshl_add_u64 v[42:43], v[4:5], 0, s[12:13]
	global_load_dwordx2 v[18:19], v[42:43], off
	s_add_u32 s12, s12, 0x40000
	s_addc_u32 s13, s13, 0
	v_lshl_add_u64 v[42:43], v[4:5], 0, s[12:13]
	global_load_dwordx2 v[20:21], v[42:43], off
	s_add_u32 s12, s12, 0x40000
	s_addc_u32 s13, s13, 0
	v_lshl_add_u64 v[42:43], v[4:5], 0, s[12:13]
	global_load_dwordx2 v[22:23], v[42:43], off
	s_add_u32 s12, s12, 0x40000
	s_addc_u32 s13, s13, 0
	v_lshl_add_u64 v[42:43], v[4:5], 0, s[12:13]
	global_load_dwordx2 v[24:25], v[42:43], off
	s_add_u32 s12, s12, 0x40000
	s_addc_u32 s13, s13, 0
	v_lshl_add_u64 v[42:43], v[4:5], 0, s[12:13]
	global_load_dwordx2 v[26:27], v[42:43], off
	s_add_u32 s12, s12, 0x40000
	s_addc_u32 s13, s13, 0
	v_lshl_add_u64 v[42:43], v[4:5], 0, s[12:13]
	global_load_dwordx2 v[28:29], v[42:43], off
	s_add_u32 s12, s12, 0x40000
	s_addc_u32 s13, s13, 0
	v_lshl_add_u64 v[42:43], v[4:5], 0, s[12:13]
	global_load_dwordx2 v[30:31], v[42:43], off
	s_add_u32 s12, s12, 0x40000
	s_addc_u32 s13, s13, 0
	v_lshl_add_u64 v[42:43], v[4:5], 0, s[12:13]
	global_load_dwordx2 v[32:33], v[42:43], off
	s_add_u32 s12, s12, 0x40000
	s_addc_u32 s13, s13, 0
	v_lshl_add_u64 v[42:43], v[4:5], 0, s[12:13]
	global_load_dwordx2 v[34:35], v[42:43], off
	s_add_u32 s12, s12, 0x40000
	s_addc_u32 s13, s13, 0
	v_lshl_add_u64 v[42:43], v[4:5], 0, s[12:13]
	global_load_dwordx2 v[36:37], v[42:43], off
	s_add_u32 s12, s12, 0x40000
	s_addc_u32 s13, s13, 0
	v_lshl_add_u64 v[42:43], v[4:5], 0, s[12:13]
	global_load_dwordx2 v[38:39], v[42:43], off
	s_add_u32 s12, s12, 0x40000
	s_addc_u32 s13, s13, 0
	v_lshl_add_u64 v[42:43], v[4:5], 0, s[12:13]
	global_load_dwordx2 v[40:41], v[42:43], off
	s_add_u32 s12, s12, 0x40000
	s_addc_u32 s13, s13, 0
	s_mov_b64 s[12:13], 0
	s_mov_b32 s11, 0
	s_waitcnt vmcnt(15)
	v_readlane_b32 s10, v8, s11
	v_lshl_add_u64 v[42:43], v[4:5], 0, s[12:13]
	global_store_dwordx2 v[42:43], v[72:73], off
	v_lshl_add_u64 v[46:47], v[44:45], 0, s[12:13]
	v_fma_f32 v72, v72, s10, v10
	v_fma_f32 v73, v73, s10, v11
	global_load_dwordx2 v[10:11], v[46:47], off
	s_add_u32 s12, s12, 0x40000
	s_addc_u32 s13, s13, 0
	s_add_i32 s11, s11, 1
	s_waitcnt vmcnt(16)
	v_readlane_b32 s10, v8, s11
	v_lshl_add_u64 v[42:43], v[4:5], 0, s[12:13]
	global_store_dwordx2 v[42:43], v[72:73], off
	v_lshl_add_u64 v[46:47], v[44:45], 0, s[12:13]
	v_fma_f32 v72, v72, s10, v12
	v_fma_f32 v73, v73, s10, v13
	global_load_dwordx2 v[12:13], v[46:47], off
	s_add_u32 s12, s12, 0x40000
	s_addc_u32 s13, s13, 0
	s_add_i32 s11, s11, 1
	s_waitcnt vmcnt(17)
	v_readlane_b32 s10, v8, s11
	v_lshl_add_u64 v[42:43], v[4:5], 0, s[12:13]
	global_store_dwordx2 v[42:43], v[72:73], off
	v_lshl_add_u64 v[46:47], v[44:45], 0, s[12:13]
	v_fma_f32 v72, v72, s10, v14
	v_fma_f32 v73, v73, s10, v15
	global_load_dwordx2 v[14:15], v[46:47], off
	s_add_u32 s12, s12, 0x40000
	s_addc_u32 s13, s13, 0
	s_add_i32 s11, s11, 1
	s_waitcnt vmcnt(18)
	v_readlane_b32 s10, v8, s11
	v_lshl_add_u64 v[42:43], v[4:5], 0, s[12:13]
	global_store_dwordx2 v[42:43], v[72:73], off
	v_lshl_add_u64 v[46:47], v[44:45], 0, s[12:13]
	v_fma_f32 v72, v72, s10, v16
	v_fma_f32 v73, v73, s10, v17
	global_load_dwordx2 v[16:17], v[46:47], off
	s_add_u32 s12, s12, 0x40000
	s_addc_u32 s13, s13, 0
	s_add_i32 s11, s11, 1
	s_waitcnt vmcnt(19)
	v_readlane_b32 s10, v8, s11
	v_lshl_add_u64 v[42:43], v[4:5], 0, s[12:13]
	global_store_dwordx2 v[42:43], v[72:73], off
	v_lshl_add_u64 v[46:47], v[44:45], 0, s[12:13]
	v_fma_f32 v72, v72, s10, v18
	v_fma_f32 v73, v73, s10, v19
	global_load_dwordx2 v[18:19], v[46:47], off
	s_add_u32 s12, s12, 0x40000
	s_addc_u32 s13, s13, 0
	s_add_i32 s11, s11, 1
	s_waitcnt vmcnt(20)
	v_readlane_b32 s10, v8, s11
	v_lshl_add_u64 v[42:43], v[4:5], 0, s[12:13]
	global_store_dwordx2 v[42:43], v[72:73], off
	v_lshl_add_u64 v[46:47], v[44:45], 0, s[12:13]
	v_fma_f32 v72, v72, s10, v20
	v_fma_f32 v73, v73, s10, v21
	global_load_dwordx2 v[20:21], v[46:47], off
	s_add_u32 s12, s12, 0x40000
	s_addc_u32 s13, s13, 0
	s_add_i32 s11, s11, 1
	s_waitcnt vmcnt(21)
	v_readlane_b32 s10, v8, s11
	v_lshl_add_u64 v[42:43], v[4:5], 0, s[12:13]
	global_store_dwordx2 v[42:43], v[72:73], off
	v_lshl_add_u64 v[46:47], v[44:45], 0, s[12:13]
	v_fma_f32 v72, v72, s10, v22
	v_fma_f32 v73, v73, s10, v23
	global_load_dwordx2 v[22:23], v[46:47], off
	s_add_u32 s12, s12, 0x40000
	s_addc_u32 s13, s13, 0
	s_add_i32 s11, s11, 1
	s_waitcnt vmcnt(22)
	v_readlane_b32 s10, v8, s11
	v_lshl_add_u64 v[42:43], v[4:5], 0, s[12:13]
	global_store_dwordx2 v[42:43], v[72:73], off
	v_lshl_add_u64 v[46:47], v[44:45], 0, s[12:13]
	v_fma_f32 v72, v72, s10, v24
	v_fma_f32 v73, v73, s10, v25
	global_load_dwordx2 v[24:25], v[46:47], off
	s_add_u32 s12, s12, 0x40000
	s_addc_u32 s13, s13, 0
	s_add_i32 s11, s11, 1
	s_waitcnt vmcnt(23)
	v_readlane_b32 s10, v8, s11
	v_lshl_add_u64 v[42:43], v[4:5], 0, s[12:13]
	global_store_dwordx2 v[42:43], v[72:73], off
	v_lshl_add_u64 v[46:47], v[44:45], 0, s[12:13]
	v_fma_f32 v72, v72, s10, v26
	v_fma_f32 v73, v73, s10, v27
	global_load_dwordx2 v[26:27], v[46:47], off
	s_add_u32 s12, s12, 0x40000
	s_addc_u32 s13, s13, 0
	s_add_i32 s11, s11, 1
	s_waitcnt vmcnt(24)
	v_readlane_b32 s10, v8, s11
	v_lshl_add_u64 v[42:43], v[4:5], 0, s[12:13]
	global_store_dwordx2 v[42:43], v[72:73], off
	v_lshl_add_u64 v[46:47], v[44:45], 0, s[12:13]
	v_fma_f32 v72, v72, s10, v28
	v_fma_f32 v73, v73, s10, v29
	global_load_dwordx2 v[28:29], v[46:47], off
	s_add_u32 s12, s12, 0x40000
	s_addc_u32 s13, s13, 0
	s_add_i32 s11, s11, 1
	s_waitcnt vmcnt(25)
	v_readlane_b32 s10, v8, s11
	v_lshl_add_u64 v[42:43], v[4:5], 0, s[12:13]
	global_store_dwordx2 v[42:43], v[72:73], off
	v_lshl_add_u64 v[46:47], v[44:45], 0, s[12:13]
	v_fma_f32 v72, v72, s10, v30
	v_fma_f32 v73, v73, s10, v31
	global_load_dwordx2 v[30:31], v[46:47], off
	s_add_u32 s12, s12, 0x40000
	s_addc_u32 s13, s13, 0
	s_add_i32 s11, s11, 1
	s_waitcnt vmcnt(26)
	v_readlane_b32 s10, v8, s11
	v_lshl_add_u64 v[42:43], v[4:5], 0, s[12:13]
	global_store_dwordx2 v[42:43], v[72:73], off
	v_lshl_add_u64 v[46:47], v[44:45], 0, s[12:13]
	v_fma_f32 v72, v72, s10, v32
	v_fma_f32 v73, v73, s10, v33
	global_load_dwordx2 v[32:33], v[46:47], off
	s_add_u32 s12, s12, 0x40000
	s_addc_u32 s13, s13, 0
	s_add_i32 s11, s11, 1
	s_waitcnt vmcnt(27)
	v_readlane_b32 s10, v8, s11
	v_lshl_add_u64 v[42:43], v[4:5], 0, s[12:13]
	global_store_dwordx2 v[42:43], v[72:73], off
	v_lshl_add_u64 v[46:47], v[44:45], 0, s[12:13]
	v_fma_f32 v72, v72, s10, v34
	v_fma_f32 v73, v73, s10, v35
	global_load_dwordx2 v[34:35], v[46:47], off
	s_add_u32 s12, s12, 0x40000
	s_addc_u32 s13, s13, 0
	s_add_i32 s11, s11, 1
	s_waitcnt vmcnt(28)
	v_readlane_b32 s10, v8, s11
	v_lshl_add_u64 v[42:43], v[4:5], 0, s[12:13]
	global_store_dwordx2 v[42:43], v[72:73], off
	v_lshl_add_u64 v[46:47], v[44:45], 0, s[12:13]
	v_fma_f32 v72, v72, s10, v36
	v_fma_f32 v73, v73, s10, v37
	global_load_dwordx2 v[36:37], v[46:47], off
	s_add_u32 s12, s12, 0x40000
	s_addc_u32 s13, s13, 0
	s_add_i32 s11, s11, 1
	s_waitcnt vmcnt(29)
	v_readlane_b32 s10, v8, s11
	v_lshl_add_u64 v[42:43], v[4:5], 0, s[12:13]
	global_store_dwordx2 v[42:43], v[72:73], off
	v_lshl_add_u64 v[46:47], v[44:45], 0, s[12:13]
	v_fma_f32 v72, v72, s10, v38
	v_fma_f32 v73, v73, s10, v39
	global_load_dwordx2 v[38:39], v[46:47], off
	s_add_u32 s12, s12, 0x40000
	s_addc_u32 s13, s13, 0
	s_add_i32 s11, s11, 1
	s_waitcnt vmcnt(30)
	v_readlane_b32 s10, v8, s11
	v_lshl_add_u64 v[42:43], v[4:5], 0, s[12:13]
	global_store_dwordx2 v[42:43], v[72:73], off
	v_lshl_add_u64 v[46:47], v[44:45], 0, s[12:13]
	v_fma_f32 v72, v72, s10, v40
	v_fma_f32 v73, v73, s10, v41
	global_load_dwordx2 v[40:41], v[46:47], off
	s_add_u32 s12, s12, 0x40000
	s_addc_u32 s13, s13, 0
	s_add_i32 s11, s11, 1
.Lscan_loop:
	s_cmp_lt_u32 s11, 64
	s_cbranch_scc0 .Lscan_hi
	s_waitcnt vmcnt(30)
	v_readlane_b32 s10, v8, s11
	v_lshl_add_u64 v[42:43], v[4:5], 0, s[12:13]
	global_store_dwordx2 v[42:43], v[72:73], off
	v_lshl_add_u64 v[46:47], v[44:45], 0, s[12:13]
	v_fma_f32 v72, v72, s10, v10
	v_fma_f32 v73, v73, s10, v11
	global_load_dwordx2 v[10:11], v[46:47], off
	s_add_u32 s12, s12, 0x40000
	s_addc_u32 s13, s13, 0
	s_add_i32 s11, s11, 1
	s_waitcnt vmcnt(30)
	v_readlane_b32 s10, v8, s11
	v_lshl_add_u64 v[42:43], v[4:5], 0, s[12:13]
	global_store_dwordx2 v[42:43], v[72:73], off
	v_lshl_add_u64 v[46:47], v[44:45], 0, s[12:13]
	v_fma_f32 v72, v72, s10, v12
	v_fma_f32 v73, v73, s10, v13
	global_load_dwordx2 v[12:13], v[46:47], off
	s_add_u32 s12, s12, 0x40000
	s_addc_u32 s13, s13, 0
	s_add_i32 s11, s11, 1
	s_waitcnt vmcnt(30)
	v_readlane_b32 s10, v8, s11
	v_lshl_add_u64 v[42:43], v[4:5], 0, s[12:13]
	global_store_dwordx2 v[42:43], v[72:73], off
	v_lshl_add_u64 v[46:47], v[44:45], 0, s[12:13]
	v_fma_f32 v72, v72, s10, v14
	v_fma_f32 v73, v73, s10, v15
	global_load_dwordx2 v[14:15], v[46:47], off
	s_add_u32 s12, s12, 0x40000
	s_addc_u32 s13, s13, 0
	s_add_i32 s11, s11, 1
	s_waitcnt vmcnt(30)
	v_readlane_b32 s10, v8, s11
	v_lshl_add_u64 v[42:43], v[4:5], 0, s[12:13]
	global_store_dwordx2 v[42:43], v[72:73], off
	v_lshl_add_u64 v[46:47], v[44:45], 0, s[12:13]
	v_fma_f32 v72, v72, s10, v16
	v_fma_f32 v73, v73, s10, v17
	global_load_dwordx2 v[16:17], v[46:47], off
	s_add_u32 s12, s12, 0x40000
	s_addc_u32 s13, s13, 0
	s_add_i32 s11, s11, 1
	s_waitcnt vmcnt(30)
	v_readlane_b32 s10, v8, s11
	v_lshl_add_u64 v[42:43], v[4:5], 0, s[12:13]
	global_store_dwordx2 v[42:43], v[72:73], off
	v_lshl_add_u64 v[46:47], v[44:45], 0, s[12:13]
	v_fma_f32 v72, v72, s10, v18
	v_fma_f32 v73, v73, s10, v19
	global_load_dwordx2 v[18:19], v[46:47], off
	s_add_u32 s12, s12, 0x40000
	s_addc_u32 s13, s13, 0
	s_add_i32 s11, s11, 1
	s_waitcnt vmcnt(30)
	v_readlane_b32 s10, v8, s11
	v_lshl_add_u64 v[42:43], v[4:5], 0, s[12:13]
	global_store_dwordx2 v[42:43], v[72:73], off
	v_lshl_add_u64 v[46:47], v[44:45], 0, s[12:13]
	v_fma_f32 v72, v72, s10, v20
	v_fma_f32 v73, v73, s10, v21
	global_load_dwordx2 v[20:21], v[46:47], off
	s_add_u32 s12, s12, 0x40000
	s_addc_u32 s13, s13, 0
	s_add_i32 s11, s11, 1
	s_waitcnt vmcnt(30)
	v_readlane_b32 s10, v8, s11
	v_lshl_add_u64 v[42:43], v[4:5], 0, s[12:13]
	global_store_dwordx2 v[42:43], v[72:73], off
	v_lshl_add_u64 v[46:47], v[44:45], 0, s[12:13]
	v_fma_f32 v72, v72, s10, v22
	v_fma_f32 v73, v73, s10, v23
	global_load_dwordx2 v[22:23], v[46:47], off
	s_add_u32 s12, s12, 0x40000
	s_addc_u32 s13, s13, 0
	s_add_i32 s11, s11, 1
	s_waitcnt vmcnt(30)
	v_readlane_b32 s10, v8, s11
	v_lshl_add_u64 v[42:43], v[4:5], 0, s[12:13]
	global_store_dwordx2 v[42:43], v[72:73], off
	v_lshl_add_u64 v[46:47], v[44:45], 0, s[12:13]
	v_fma_f32 v72, v72, s10, v24
	v_fma_f32 v73, v73, s10, v25
	global_load_dwordx2 v[24:25], v[46:47], off
	s_add_u32 s12, s12, 0x40000
	s_addc_u32 s13, s13, 0
	s_add_i32 s11, s11, 1
	s_waitcnt vmcnt(30)
	v_readlane_b32 s10, v8, s11
	v_lshl_add_u64 v[42:43], v[4:5], 0, s[12:13]
	global_store_dwordx2 v[42:43], v[72:73], off
	v_lshl_add_u64 v[46:47], v[44:45], 0, s[12:13]
	v_fma_f32 v72, v72, s10, v26
	v_fma_f32 v73, v73, s10, v27
	global_load_dwordx2 v[26:27], v[46:47], off
	s_add_u32 s12, s12, 0x40000
	s_addc_u32 s13, s13, 0
	s_add_i32 s11, s11, 1
	s_waitcnt vmcnt(30)
	v_readlane_b32 s10, v8, s11
	v_lshl_add_u64 v[42:43], v[4:5], 0, s[12:13]
	global_store_dwordx2 v[42:43], v[72:73], off
	v_lshl_add_u64 v[46:47], v[44:45], 0, s[12:13]
	v_fma_f32 v72, v72, s10, v28
	v_fma_f32 v73, v73, s10, v29
	global_load_dwordx2 v[28:29], v[46:47], off
	s_add_u32 s12, s12, 0x40000
	s_addc_u32 s13, s13, 0
	s_add_i32 s11, s11, 1
	s_waitcnt vmcnt(30)
	v_readlane_b32 s10, v8, s11
	v_lshl_add_u64 v[42:43], v[4:5], 0, s[12:13]
	global_store_dwordx2 v[42:43], v[72:73], off
	v_lshl_add_u64 v[46:47], v[44:45], 0, s[12:13]
	v_fma_f32 v72, v72, s10, v30
	v_fma_f32 v73, v73, s10, v31
	global_load_dwordx2 v[30:31], v[46:47], off
	s_add_u32 s12, s12, 0x40000
	s_addc_u32 s13, s13, 0
	s_add_i32 s11, s11, 1
	s_waitcnt vmcnt(30)
	v_readlane_b32 s10, v8, s11
	v_lshl_add_u64 v[42:43], v[4:5], 0, s[12:13]
	global_store_dwordx2 v[42:43], v[72:73], off
	v_lshl_add_u64 v[46:47], v[44:45], 0, s[12:13]
	v_fma_f32 v72, v72, s10, v32
	v_fma_f32 v73, v73, s10, v33
	global_load_dwordx2 v[32:33], v[46:47], off
	s_add_u32 s12, s12, 0x40000
	s_addc_u32 s13, s13, 0
	s_add_i32 s11, s11, 1
	s_waitcnt vmcnt(30)
	v_readlane_b32 s10, v8, s11
	v_lshl_add_u64 v[42:43], v[4:5], 0, s[12:13]
	global_store_dwordx2 v[42:43], v[72:73], off
	v_lshl_add_u64 v[46:47], v[44:45], 0, s[12:13]
	v_fma_f32 v72, v72, s10, v34
	v_fma_f32 v73, v73, s10, v35
	global_load_dwordx2 v[34:35], v[46:47], off
	s_add_u32 s12, s12, 0x40000
	s_addc_u32 s13, s13, 0
	s_add_i32 s11, s11, 1
	s_waitcnt vmcnt(30)
	v_readlane_b32 s10, v8, s11
	v_lshl_add_u64 v[42:43], v[4:5], 0, s[12:13]
	global_store_dwordx2 v[42:43], v[72:73], off
	v_lshl_add_u64 v[46:47], v[44:45], 0, s[12:13]
	v_fma_f32 v72, v72, s10, v36
	v_fma_f32 v73, v73, s10, v37
	global_load_dwordx2 v[36:37], v[46:47], off
	s_add_u32 s12, s12, 0x40000
	s_addc_u32 s13, s13, 0
	s_add_i32 s11, s11, 1
	s_waitcnt vmcnt(30)
	v_readlane_b32 s10, v8, s11
	v_lshl_add_u64 v[42:43], v[4:5], 0, s[12:13]
	global_store_dwordx2 v[42:43], v[72:73], off
	v_lshl_add_u64 v[46:47], v[44:45], 0, s[12:13]
	v_fma_f32 v72, v72, s10, v38
	v_fma_f32 v73, v73, s10, v39
	global_load_dwordx2 v[38:39], v[46:47], off
	s_add_u32 s12, s12, 0x40000
	s_addc_u32 s13, s13, 0
	s_add_i32 s11, s11, 1
	s_waitcnt vmcnt(30)
	v_readlane_b32 s10, v8, s11
	v_lshl_add_u64 v[42:43], v[4:5], 0, s[12:13]
	global_store_dwordx2 v[42:43], v[72:73], off
	v_lshl_add_u64 v[46:47], v[44:45], 0, s[12:13]
	v_fma_f32 v72, v72, s10, v40
	v_fma_f32 v73, v73, s10, v41
	global_load_dwordx2 v[40:41], v[46:47], off
	s_add_u32 s12, s12, 0x40000
	s_addc_u32 s13, s13, 0
	s_add_i32 s11, s11, 1
	s_branch .Lscan_next
.Lscan_hi:
	s_sub_i32 s11, s11, 64
	s_waitcnt vmcnt(30)
	v_readlane_b32 s10, v9, s11
	v_lshl_add_u64 v[42:43], v[4:5], 0, s[12:13]
	global_store_dwordx2 v[42:43], v[72:73], off
	v_lshl_add_u64 v[46:47], v[44:45], 0, s[12:13]
	v_fma_f32 v72, v72, s10, v10
	v_fma_f32 v73, v73, s10, v11
	global_load_dwordx2 v[10:11], v[46:47], off
	s_add_u32 s12, s12, 0x40000
	s_addc_u32 s13, s13, 0
	s_add_i32 s11, s11, 1
	s_waitcnt vmcnt(30)
	v_readlane_b32 s10, v9, s11
	v_lshl_add_u64 v[42:43], v[4:5], 0, s[12:13]
	global_store_dwordx2 v[42:43], v[72:73], off
	v_lshl_add_u64 v[46:47], v[44:45], 0, s[12:13]
	v_fma_f32 v72, v72, s10, v12
	v_fma_f32 v73, v73, s10, v13
	global_load_dwordx2 v[12:13], v[46:47], off
	s_add_u32 s12, s12, 0x40000
	s_addc_u32 s13, s13, 0
	s_add_i32 s11, s11, 1
	s_waitcnt vmcnt(30)
	v_readlane_b32 s10, v9, s11
	v_lshl_add_u64 v[42:43], v[4:5], 0, s[12:13]
	global_store_dwordx2 v[42:43], v[72:73], off
	v_lshl_add_u64 v[46:47], v[44:45], 0, s[12:13]
	v_fma_f32 v72, v72, s10, v14
	v_fma_f32 v73, v73, s10, v15
	global_load_dwordx2 v[14:15], v[46:47], off
	s_add_u32 s12, s12, 0x40000
	s_addc_u32 s13, s13, 0
	s_add_i32 s11, s11, 1
	s_waitcnt vmcnt(30)
	v_readlane_b32 s10, v9, s11
	v_lshl_add_u64 v[42:43], v[4:5], 0, s[12:13]
	global_store_dwordx2 v[42:43], v[72:73], off
	v_lshl_add_u64 v[46:47], v[44:45], 0, s[12:13]
	v_fma_f32 v72, v72, s10, v16
	v_fma_f32 v73, v73, s10, v17
	global_load_dwordx2 v[16:17], v[46:47], off
	s_add_u32 s12, s12, 0x40000
	s_addc_u32 s13, s13, 0
	s_add_i32 s11, s11, 1
	s_waitcnt vmcnt(30)
	v_readlane_b32 s10, v9, s11
	v_lshl_add_u64 v[42:43], v[4:5], 0, s[12:13]
	global_store_dwordx2 v[42:43], v[72:73], off
	v_lshl_add_u64 v[46:47], v[44:45], 0, s[12:13]
	v_fma_f32 v72, v72, s10, v18
	v_fma_f32 v73, v73, s10, v19
	global_load_dwordx2 v[18:19], v[46:47], off
	s_add_u32 s12, s12, 0x40000
	s_addc_u32 s13, s13, 0
	s_add_i32 s11, s11, 1
	s_waitcnt vmcnt(30)
	v_readlane_b32 s10, v9, s11
	v_lshl_add_u64 v[42:43], v[4:5], 0, s[12:13]
	global_store_dwordx2 v[42:43], v[72:73], off
	v_lshl_add_u64 v[46:47], v[44:45], 0, s[12:13]
	v_fma_f32 v72, v72, s10, v20
	v_fma_f32 v73, v73, s10, v21
	global_load_dwordx2 v[20:21], v[46:47], off
	s_add_u32 s12, s12, 0x40000
	s_addc_u32 s13, s13, 0
	s_add_i32 s11, s11, 1
	s_waitcnt vmcnt(30)
	v_readlane_b32 s10, v9, s11
	v_lshl_add_u64 v[42:43], v[4:5], 0, s[12:13]
	global_store_dwordx2 v[42:43], v[72:73], off
	v_lshl_add_u64 v[46:47], v[44:45], 0, s[12:13]
	v_fma_f32 v72, v72, s10, v22
	v_fma_f32 v73, v73, s10, v23
	global_load_dwordx2 v[22:23], v[46:47], off
	s_add_u32 s12, s12, 0x40000
	s_addc_u32 s13, s13, 0
	s_add_i32 s11, s11, 1
	s_waitcnt vmcnt(30)
	v_readlane_b32 s10, v9, s11
	v_lshl_add_u64 v[42:43], v[4:5], 0, s[12:13]
	global_store_dwordx2 v[42:43], v[72:73], off
	v_lshl_add_u64 v[46:47], v[44:45], 0, s[12:13]
	v_fma_f32 v72, v72, s10, v24
	v_fma_f32 v73, v73, s10, v25
	global_load_dwordx2 v[24:25], v[46:47], off
	s_add_u32 s12, s12, 0x40000
	s_addc_u32 s13, s13, 0
	s_add_i32 s11, s11, 1
	s_waitcnt vmcnt(30)
	v_readlane_b32 s10, v9, s11
	v_lshl_add_u64 v[42:43], v[4:5], 0, s[12:13]
	global_store_dwordx2 v[42:43], v[72:73], off
	v_lshl_add_u64 v[46:47], v[44:45], 0, s[12:13]
	v_fma_f32 v72, v72, s10, v26
	v_fma_f32 v73, v73, s10, v27
	global_load_dwordx2 v[26:27], v[46:47], off
	s_add_u32 s12, s12, 0x40000
	s_addc_u32 s13, s13, 0
	s_add_i32 s11, s11, 1
	s_waitcnt vmcnt(30)
	v_readlane_b32 s10, v9, s11
	v_lshl_add_u64 v[42:43], v[4:5], 0, s[12:13]
	global_store_dwordx2 v[42:43], v[72:73], off
	v_lshl_add_u64 v[46:47], v[44:45], 0, s[12:13]
	v_fma_f32 v72, v72, s10, v28
	v_fma_f32 v73, v73, s10, v29
	global_load_dwordx2 v[28:29], v[46:47], off
	s_add_u32 s12, s12, 0x40000
	s_addc_u32 s13, s13, 0
	s_add_i32 s11, s11, 1
	s_waitcnt vmcnt(30)
	v_readlane_b32 s10, v9, s11
	v_lshl_add_u64 v[42:43], v[4:5], 0, s[12:13]
	global_store_dwordx2 v[42:43], v[72:73], off
	v_lshl_add_u64 v[46:47], v[44:45], 0, s[12:13]
	v_fma_f32 v72, v72, s10, v30
	v_fma_f32 v73, v73, s10, v31
	global_load_dwordx2 v[30:31], v[46:47], off
	s_add_u32 s12, s12, 0x40000
	s_addc_u32 s13, s13, 0
	s_add_i32 s11, s11, 1
	s_waitcnt vmcnt(30)
	v_readlane_b32 s10, v9, s11
	v_lshl_add_u64 v[42:43], v[4:5], 0, s[12:13]
	global_store_dwordx2 v[42:43], v[72:73], off
	v_lshl_add_u64 v[46:47], v[44:45], 0, s[12:13]
	v_fma_f32 v72, v72, s10, v32
	v_fma_f32 v73, v73, s10, v33
	global_load_dwordx2 v[32:33], v[46:47], off
	s_add_u32 s12, s12, 0x40000
	s_addc_u32 s13, s13, 0
	s_add_i32 s11, s11, 1
	s_waitcnt vmcnt(30)
	v_readlane_b32 s10, v9, s11
	v_lshl_add_u64 v[42:43], v[4:5], 0, s[12:13]
	global_store_dwordx2 v[42:43], v[72:73], off
	v_lshl_add_u64 v[46:47], v[44:45], 0, s[12:13]
	v_fma_f32 v72, v72, s10, v34
	v_fma_f32 v73, v73, s10, v35
	global_load_dwordx2 v[34:35], v[46:47], off
	s_add_u32 s12, s12, 0x40000
	s_addc_u32 s13, s13, 0
	s_add_i32 s11, s11, 1
	s_waitcnt vmcnt(30)
	v_readlane_b32 s10, v9, s11
	v_lshl_add_u64 v[42:43], v[4:5], 0, s[12:13]
	global_store_dwordx2 v[42:43], v[72:73], off
	v_lshl_add_u64 v[46:47], v[44:45], 0, s[12:13]
	v_fma_f32 v72, v72, s10, v36
	v_fma_f32 v73, v73, s10, v37
	global_load_dwordx2 v[36:37], v[46:47], off
	s_add_u32 s12, s12, 0x40000
	s_addc_u32 s13, s13, 0
	s_add_i32 s11, s11, 1
	s_waitcnt vmcnt(30)
	v_readlane_b32 s10, v9, s11
	v_lshl_add_u64 v[42:43], v[4:5], 0, s[12:13]
	global_store_dwordx2 v[42:43], v[72:73], off
	v_lshl_add_u64 v[46:47], v[44:45], 0, s[12:13]
	v_fma_f32 v72, v72, s10, v38
	v_fma_f32 v73, v73, s10, v39
	global_load_dwordx2 v[38:39], v[46:47], off
	s_add_u32 s12, s12, 0x40000
	s_addc_u32 s13, s13, 0
	s_add_i32 s11, s11, 1
	s_waitcnt vmcnt(30)
	v_readlane_b32 s10, v9, s11
	v_lshl_add_u64 v[42:43], v[4:5], 0, s[12:13]
	global_store_dwordx2 v[42:43], v[72:73], off
	v_lshl_add_u64 v[46:47], v[44:45], 0, s[12:13]
	v_fma_f32 v72, v72, s10, v40
	v_fma_f32 v73, v73, s10, v41
	global_load_dwordx2 v[40:41], v[46:47], off
	s_add_u32 s12, s12, 0x40000
	s_addc_u32 s13, s13, 0
	s_add_i32 s11, s11, 1
	s_add_i32 s11, s11, 64
.Lscan_next:
	s_cmp_lt_u32 s11, 112
	s_cbranch_scc1 .Lscan_loop
	s_sub_i32 s11, s11, 64
	s_waitcnt vmcnt(30)
	v_readlane_b32 s10, v9, s11
	v_lshl_add_u64 v[42:43], v[4:5], 0, s[12:13]
	global_store_dwordx2 v[42:43], v[72:73], off
	v_fma_f32 v72, v72, s10, v10
	v_fma_f32 v73, v73, s10, v11
	s_add_u32 s12, s12, 0x40000
	s_addc_u32 s13, s13, 0
	s_add_i32 s11, s11, 1
	s_waitcnt vmcnt(29)
	v_readlane_b32 s10, v9, s11
	v_lshl_add_u64 v[42:43], v[4:5], 0, s[12:13]
	global_store_dwordx2 v[42:43], v[72:73], off
	v_fma_f32 v72, v72, s10, v12
	v_fma_f32 v73, v73, s10, v13
	s_add_u32 s12, s12, 0x40000
	s_addc_u32 s13, s13, 0
	s_add_i32 s11, s11, 1
	s_waitcnt vmcnt(28)
	v_readlane_b32 s10, v9, s11
	v_lshl_add_u64 v[42:43], v[4:5], 0, s[12:13]
	global_store_dwordx2 v[42:43], v[72:73], off
	v_fma_f32 v72, v72, s10, v14
	v_fma_f32 v73, v73, s10, v15
	s_add_u32 s12, s12, 0x40000
	s_addc_u32 s13, s13, 0
	s_add_i32 s11, s11, 1
	s_waitcnt vmcnt(27)
	v_readlane_b32 s10, v9, s11
	v_lshl_add_u64 v[42:43], v[4:5], 0, s[12:13]
	global_store_dwordx2 v[42:43], v[72:73], off
	v_fma_f32 v72, v72, s10, v16
	v_fma_f32 v73, v73, s10, v17
	s_add_u32 s12, s12, 0x40000
	s_addc_u32 s13, s13, 0
	s_add_i32 s11, s11, 1
	s_waitcnt vmcnt(26)
	v_readlane_b32 s10, v9, s11
	v_lshl_add_u64 v[42:43], v[4:5], 0, s[12:13]
	global_store_dwordx2 v[42:43], v[72:73], off
	v_fma_f32 v72, v72, s10, v18
	v_fma_f32 v73, v73, s10, v19
	s_add_u32 s12, s12, 0x40000
	s_addc_u32 s13, s13, 0
	s_add_i32 s11, s11, 1
	s_waitcnt vmcnt(25)
	v_readlane_b32 s10, v9, s11
	v_lshl_add_u64 v[42:43], v[4:5], 0, s[12:13]
	global_store_dwordx2 v[42:43], v[72:73], off
	v_fma_f32 v72, v72, s10, v20
	v_fma_f32 v73, v73, s10, v21
	s_add_u32 s12, s12, 0x40000
	s_addc_u32 s13, s13, 0
	s_add_i32 s11, s11, 1
	s_waitcnt vmcnt(24)
	v_readlane_b32 s10, v9, s11
	v_lshl_add_u64 v[42:43], v[4:5], 0, s[12:13]
	global_store_dwordx2 v[42:43], v[72:73], off
	v_fma_f32 v72, v72, s10, v22
	v_fma_f32 v73, v73, s10, v23
	s_add_u32 s12, s12, 0x40000
	s_addc_u32 s13, s13, 0
	s_add_i32 s11, s11, 1
	s_waitcnt vmcnt(23)
	v_readlane_b32 s10, v9, s11
	v_lshl_add_u64 v[42:43], v[4:5], 0, s[12:13]
	global_store_dwordx2 v[42:43], v[72:73], off
	v_fma_f32 v72, v72, s10, v24
	v_fma_f32 v73, v73, s10, v25
	s_add_u32 s12, s12, 0x40000
	s_addc_u32 s13, s13, 0
	s_add_i32 s11, s11, 1
	s_waitcnt vmcnt(22)
	v_readlane_b32 s10, v9, s11
	v_lshl_add_u64 v[42:43], v[4:5], 0, s[12:13]
	global_store_dwordx2 v[42:43], v[72:73], off
	v_fma_f32 v72, v72, s10, v26
	v_fma_f32 v73, v73, s10, v27
	s_add_u32 s12, s12, 0x40000
	s_addc_u32 s13, s13, 0
	s_add_i32 s11, s11, 1
	s_waitcnt vmcnt(21)
	v_readlane_b32 s10, v9, s11
	v_lshl_add_u64 v[42:43], v[4:5], 0, s[12:13]
	global_store_dwordx2 v[42:43], v[72:73], off
	v_fma_f32 v72, v72, s10, v28
	v_fma_f32 v73, v73, s10, v29
	s_add_u32 s12, s12, 0x40000
	s_addc_u32 s13, s13, 0
	s_add_i32 s11, s11, 1
	s_waitcnt vmcnt(20)
	v_readlane_b32 s10, v9, s11
	v_lshl_add_u64 v[42:43], v[4:5], 0, s[12:13]
	global_store_dwordx2 v[42:43], v[72:73], off
	v_fma_f32 v72, v72, s10, v30
	v_fma_f32 v73, v73, s10, v31
	s_add_u32 s12, s12, 0x40000
	s_addc_u32 s13, s13, 0
	s_add_i32 s11, s11, 1
	s_waitcnt vmcnt(19)
	v_readlane_b32 s10, v9, s11
	v_lshl_add_u64 v[42:43], v[4:5], 0, s[12:13]
	global_store_dwordx2 v[42:43], v[72:73], off
	v_fma_f32 v72, v72, s10, v32
	v_fma_f32 v73, v73, s10, v33
	s_add_u32 s12, s12, 0x40000
	s_addc_u32 s13, s13, 0
	s_add_i32 s11, s11, 1
	s_waitcnt vmcnt(18)
	v_readlane_b32 s10, v9, s11
	v_lshl_add_u64 v[42:43], v[4:5], 0, s[12:13]
	global_store_dwordx2 v[42:43], v[72:73], off
	v_fma_f32 v72, v72, s10, v34
	v_fma_f32 v73, v73, s10, v35
	s_add_u32 s12, s12, 0x40000
	s_addc_u32 s13, s13, 0
	s_add_i32 s11, s11, 1
	s_waitcnt vmcnt(17)
	v_readlane_b32 s10, v9, s11
	v_lshl_add_u64 v[42:43], v[4:5], 0, s[12:13]
	global_store_dwordx2 v[42:43], v[72:73], off
	v_fma_f32 v72, v72, s10, v36
	v_fma_f32 v73, v73, s10, v37
	s_add_u32 s12, s12, 0x40000
	s_addc_u32 s13, s13, 0
	s_add_i32 s11, s11, 1
	s_waitcnt vmcnt(16)
	v_readlane_b32 s10, v9, s11
	v_lshl_add_u64 v[42:43], v[4:5], 0, s[12:13]
	global_store_dwordx2 v[42:43], v[72:73], off
	v_fma_f32 v72, v72, s10, v38
	v_fma_f32 v73, v73, s10, v39
	s_add_u32 s12, s12, 0x40000
	s_addc_u32 s13, s13, 0
	s_add_i32 s11, s11, 1
	s_waitcnt vmcnt(15)
	v_readlane_b32 s10, v9, s11
	v_lshl_add_u64 v[42:43], v[4:5], 0, s[12:13]
	global_store_dwordx2 v[42:43], v[72:73], off
	v_fma_f32 v72, v72, s10, v40
	v_fma_f32 v73, v73, s10, v41
	s_add_u32 s12, s12, 0x40000
	s_addc_u32 s13, s13, 0
	s_add_i32 s11, s11, 1
	v_lshlrev_b32_e32 v4, 1, v74
	v_add_u32_e32 v74, s4, v74
	v_ashrrev_i32_e32 v5, 31, v4
	v_cmp_lt_i32_e32 vcc, s14, v74
	v_lshl_add_u64 v[4:5], v[4:5], 2, s[6:7]
	s_or_b64 s[8:9], vcc, s[8:9]
	v_add_u32_e32 v75, s5, v75
	global_store_dwordx2 v[4:5], v[72:73], off
	s_andn2_b64 exec, exec, s[8:9]
	s_cbranch_execnz .LBB0_1888
